# phase ends: duplicate workgroup barrier in front of the phase-end vmcnt0+barrier dropped at 4 sites (on top of the sample-epilogue tidy)
# baseline (speedup 1.0000x reference)
; #define PG8_WAIT_V(n) asm volatile("s_waitcnt vmcnt(" #n ")" ::: "memory")
; #define PG8_BAR __builtin_amdgcn_s_barrier()
; __device__ __forceinline__ unsigned xb_ld(unsigned* p)              { return __hip_atomic_load(p, __ATOMIC_RELAXED, __HIP_MEMORY_SCOPE_AGENT); }
; __device__ __forceinline__ unsigned xb_xcc_id() { return (unsigned)__builtin_amdgcn_s_getreg((3 << 11) | 20) & 0xFu; }
; template <class Epi, bool ALIGN_EPI, bool SP2, class Ord = StaticOrder>
; __device__ __forceinline__ void gemm_phase(LAS unsigned char* lds, const Gemm g, const Ord& S, const Epi& E) {
;     ...
;     PG8_WAIT_V(0);
;     if constexpr (!ALIGN_EPI) { if (wr == 0) PG8_BAR; }
;     PG8_BAR;
; __device__ __forceinline__ void xcd_barrier_complete(unsigned* bar, unsigned x, unsigned& nloc, unsigned& nx) {
;     const unsigned G = gridDim.x * gridDim.y * gridDim.z;
;     unsigned sum, cnt, mine, sp = 0u;
;     for (;;) {
;         sum = 0u; cnt = 0u; mine = 0u;
; #pragma unroll
;         for (unsigned j = 0; j < 16; ++j) { const unsigned c = xb_ld(&bar[XB_XCNT(j)]); sum += c; cnt += (c > 0u) ? 1u : 0u; mine = (j == x) ? c : mine; }
;         if (sum == G) break;
;         __builtin_amdgcn_s_sleep(1);
;         if ((++sp & 255u) == 0u) { if (xb_ld(&bar[XB_TMO])) break; if (sp > XB_SPIN_CAP) { atomicAdd(&bar[XB_TMO], 1u); break; } }
;     }
;     nloc = mine > 0u ? mine : 1u; nx = cnt > 0u ? cnt : 1u;
; }
; __device__ __forceinline__ void xcd_barrier(const XcdBarrier& b) {
;     asm volatile("s_waitcnt vmcnt(0)" ::: "memory");
;     __syncthreads();
;     if (threadIdx.x == 0) {
;         unsigned* bar = b.bar;
;         unsigned bx_ = (unsigned)__builtin_amdgcn_readfirstlane((int)xb_xcc_id()); asm volatile("" : "+s"(bx_));
;         __builtin_amdgcn_s_waitcnt(0);
;         unsigned nloc = b.st[0], nx = b.st[1];
;         if (nloc == 0u) { xcd_barrier_complete(bar, bx_, nloc, nx); b.st[0] = nloc; b.st[1] = nx; }
.LBB0_381:
	s_waitcnt vmcnt(0)
.LBB0_382:
	s_waitcnt vmcnt(0)
	s_waitcnt vmcnt(0) lgkmcnt(0)
	s_barrier
	s_and_saveexec_b64 s[0:1], s[66:67]
	s_xor_b64 s[0:1], exec, s[0:1]
	s_cbranch_execz .LBB0_435
	s_getreg_b32 s2, hwreg(HW_REG_XCC_ID, 0, 4)
	s_add_i32 s3, 0, 0x27fc0
	s_and_b32 s2, s2, 15
	v_mov_b32_e32 v1, s3
	s_waitcnt vmcnt(0) expcnt(0) lgkmcnt(0)
	ds_read_b32 v3, v1
	s_add_i32 s3, 0, 0x27fc4
	v_mov_b32_e32 v1, s3
	ds_read_b32 v1, v1
	s_waitcnt lgkmcnt(1)
	v_cmp_ne_u32_e32 vcc, 0, v3
	s_cbranch_vccnz .LBB0_398
	v_readlane_b32 s36, v245, 19
	v_readlane_b32 s50, v245, 33
	v_readlane_b32 s51, v245, 34
	s_add_u32 s4, s50, 0x1200
	s_addc_u32 s5, s51, 0
	s_add_u32 s6, s50, 0x1400
	s_addc_u32 s7, s51, 0
	s_add_u32 s8, s50, 0x1500
	s_addc_u32 s9, s51, 0
	s_add_u32 s14, s50, 0x1600
	s_addc_u32 s15, s51, 0
	s_add_u32 s16, s50, 0x1700
	s_addc_u32 s17, s51, 0
	s_add_u32 s18, s50, 0x1800
	s_addc_u32 s19, s51, 0
	s_add_u32 s20, s50, 0x1900
	s_addc_u32 s21, s51, 0
	s_add_u32 s22, s50, 0x1a00
	s_addc_u32 s23, s51, 0
	s_add_u32 s24, s50, 0x1b00
	s_addc_u32 s25, s51, 0
	s_add_u32 s28, s50, 0x1c00
	s_addc_u32 s29, s51, 0
	s_add_u32 s30, s50, 0x1d00
	s_addc_u32 s31, s51, 0
	s_add_u32 s34, s50, 0x1e00
	s_addc_u32 s35, s51, 0
	v_readlane_b32 s37, v245, 20
	s_add_u32 s36, s50, 0x1f00
	v_readlane_b32 s38, v245, 21
	s_addc_u32 s37, s51, 0
	v_readlane_b32 s39, v245, 22
	s_add_u32 s38, s50, 0x2000
	v_readlane_b32 s40, v245, 23
	s_addc_u32 s39, s51, 0
	v_readlane_b32 s41, v245, 24
	s_add_u32 s40, s50, 0x2100
	v_readlane_b32 s42, v245, 25
	s_addc_u32 s41, s51, 0
	v_readlane_b32 s43, v245, 26
	s_add_u32 s42, s50, 0x2200
	v_readlane_b32 s44, v245, 27
	s_addc_u32 s43, s51, 0
	s_mul_i32 s3, s97, s93
	v_readlane_b32 s45, v245, 28
	s_add_u32 s44, s50, 0x2300
	s_mul_i32 s3, s3, s96
	s_addc_u32 s45, s51, 0
	s_mov_b32 s26, 1
	v_mov_b32_e32 v17, 0
	v_readlane_b32 s46, v245, 29
	v_readlane_b32 s47, v245, 30
	v_readlane_b32 s48, v245, 31
	v_readlane_b32 s49, v245, 32
	s_branch .LBB0_386

; #define LAS __attribute__((address_space(3)))
; __device__ __forceinline__ void gdn_prep_item(LAS unsigned char* lds, int item, int b0, PrepRaw& R, int next_item, const bf16_t* qkv, const float* bg, const float* gconv_w, unsigned char* rec, float* gtarr) {
;     ...
;     {
;         const f32x4 z4 = (f32x4){0.f, 0.f, 0.f, 0.f};
; #pragma unroll
;         for (int rt = 0; rt < 4; ++rt) { f32x4 acc = z4;
; #pragma unroll
;             for (int s = 0; s < 2; ++s) { const bf16x8 tf = *(const LAS bf16x8*)(lds + P2_TB + ((16 * rt + l15) * 72 + 32 * s + 8 * g) * 2), vf = *(const LAS bf16x8*)(lds + P2_VBT + ((16 * wave + l15) * 72 + 32 * s + 8 * g) * 2);
;                 acc = MFMA16(tf, vf, acc); }
;             u32x2 w; w.x = cvt_pk_bf16(acc[0], acc[1]); w.y = cvt_pk_bf16(acc[2], acc[3]);
;             *(u32x2*)(rec + REC_U + ((rt * 8 + wave) * 64 + lane) * 8) = w; }
;         const int rt = wave >> 1;
; #pragma unroll
;         for (int q = 0; q < 2; ++q) { const int s2 = 2 * (wave & 1) + q; f32x4 a0 = z4, a1 = z4;
; #pragma unroll
;             for (int s = 0; s < 2; ++s) { const bf16x8 tf = *(const LAS bf16x8*)(lds + P2_TB + ((16 * rt + l15) * 72 + 32 * s + 8 * g) * 2);
;                 const bf16x8 k0 = *(const LAS bf16x8*)(lds + P2_KBT + ((32 * s2 + l15) * 72 + 32 * s + 8 * g) * 2), k1 = *(const LAS bf16x8*)(lds + P2_KBT + ((32 * s2 + 16 + l15) * 72 + 32 * s + 8 * g) * 2);
;                 a0 = MFMA16(k0, tf, a0); a1 = MFMA16(k1, tf, a1); }
;             *(bf16x8*)(rec + REC_WN + ((rt * 4 + s2) * 64 + lane) * 16) = pack8(-a0, -a1); }
;     }
; #pragma unroll
;     for (int q = 0; q < 2; ++q) { const int task = tid + q * NTHREADS, fragi = task >> 6, ln = task & 63, lg = ln >> 4, l = ln & 15;
;         const int rt = fragi >> 2, s2 = fragi & 3, i = 16 * rt + l; const float e = EG[i];
;         const u32x2 lo = *(const LAS u32x2*)(lds + P2_QN + (i * 136 + 32 * s2 + 4 * lg) * 2), hi = *(const LAS u32x2*)(lds + P2_QN + (i * 136 + 32 * s2 + 16 + 4 * lg) * 2);
;         const unsigned vv[4] = {lo.x, lo.y, hi.x, hi.y}; u32x4 w; unsigned ww[4];
; #pragma unroll
;         for (int k2 = 0; k2 < 4; ++k2) ww[k2] = cvt_pk_bf16(__uint_as_float(vv[k2] << 16) * e, __uint_as_float(vv[k2] & 0xffff0000u) * e);
;         w.x = ww[0]; w.y = ww[1]; w.z = ww[2]; w.w = ww[3];
;         *(u32x4*)(rec + REC_QD + (fragi * 64 + ln) * 16) = w; }
.LBB0_700:
	s_or_b64 exec, exec, s[0:1]
	s_movk_i32 s8, 0x48
	s_add_u32 s0, s4, 0xe000
	s_addc_u32 s1, s5, 0
	v_mad_u32_u24 v2, v1, s8, v10
	s_add_i32 s9, 0, 0x1a000
	v_lshl_add_u32 v38, v2, 1, s9
	s_waitcnt lgkmcnt(0)
	s_barrier
	ds_read_b128 v[2:5], v38
	v_lshl_or_b32 v9, s20, 4, v1
	s_and_b32 s98, s20, 1
	s_lshl_b32 s98, s98, 4
	v_and_or_b32 v248, v1, 8, s98
	v_xor_b32_e32 v248, v248, v10
	v_mad_u32_u24 v12, v9, s8, v248
	v_lshl_add_u32 v9, v12, 1, 0
	ds_read_b128 v[12:15], v38 offset:64
	ds_read_b128 v[16:19], v9 offset:34816
	ds_read_b128 v[20:23], v9 offset:34880
	s_waitcnt lgkmcnt(1)
	v_mfma_f32_16x16x32_bf16 v[2:5], v[2:5], v[16:19], 0
	ds_read_b128 v[24:27], v38 offset:2304
	v_or_b32_e32 v9, 0x480, v10
	v_and_b32_e32 v249, 8, v1
	v_xor_b32_e32 v249, v249, v10
	v_xor_b32_e32 v250, 16, v249
	v_or_b32_e32 v250, 0x480, v250
	v_lshl_or_b32 v7, s22, 12, v7
	s_waitcnt lgkmcnt(1)
	v_mfma_f32_16x16x32_bf16 v[2:5], v[12:15], v[20:23], v[2:5]
	ds_read_b128 v[12:15], v38 offset:2368
	s_nop 6
	v_cvt_pk_bf16_f32 v28, v2, v3
	v_lshlrev_b32_e32 v2, 3, v101
	v_lshl_or_b32 v36, s20, 9, v2
	v_ashrrev_i32_e32 v37, 31, v36
	v_cvt_pk_bf16_f32 v29, v4, v5
	s_waitcnt lgkmcnt(1)
	v_mfma_f32_16x16x32_bf16 v[2:5], v[24:27], v[16:19], 0
	v_lshl_add_u64 v[24:25], s[0:1], 0, v[36:37]
	global_store_dwordx2 v[24:25], v[28:29], off sc0 sc1
	ds_read_b128 v[24:27], v38 offset:4608
	s_waitcnt lgkmcnt(1)
	v_mfma_f32_16x16x32_bf16 v[2:5], v[12:15], v[20:23], v[2:5]
	ds_read_b128 v[12:15], v38 offset:4672
	v_add_u32_e32 v30, 0x1000, v36
	v_ashrrev_i32_e32 v31, 31, v30
	v_add_u32_e32 v34, 0x2000, v36
	v_ashrrev_i32_e32 v35, 31, v34
	s_nop 2
	v_cvt_pk_bf16_f32 v28, v2, v3
	v_cvt_pk_bf16_f32 v29, v4, v5
	s_waitcnt lgkmcnt(1)
	v_mfma_f32_16x16x32_bf16 v[2:5], v[24:27], v[16:19], 0
	v_lshl_add_u64 v[24:25], s[0:1], 0, v[30:31]
	global_store_dwordx2 v[24:25], v[28:29], off sc0 sc1
	ds_read_b128 v[24:27], v38 offset:6912
	s_waitcnt lgkmcnt(1)
	v_mfma_f32_16x16x32_bf16 v[2:5], v[12:15], v[20:23], v[2:5]
	v_lshl_add_u64 v[34:35], s[0:1], 0, v[34:35]
	v_add_u32_e32 v36, 0x3000, v36
	s_nop 5
	v_cvt_pk_bf16_f32 v32, v2, v3
	v_cvt_pk_bf16_f32 v33, v4, v5
	ds_read_b128 v[2:5], v38 offset:6976
	s_waitcnt lgkmcnt(1)
	v_mfma_f32_16x16x32_bf16 v[12:15], v[24:27], v[16:19], 0
	v_mad_u64_u32 v[16:17], s[6:7], v11, s8, v[10:11]
	v_lshl_or_b32 v24, s23, 6, v1
	v_lshl_add_u32 v11, v16, 1, s9
	v_mad_u32_u24 v16, v24, s8, v249
	v_lshl_add_u32 v37, v16, 1, 0
	v_mad_u32_u24 v28, v24, s8, v250
	ds_read_b128 v[16:19], v37 offset:53248
	ds_read_b128 v[24:27], v11
	v_lshl_add_u32 v39, v28, 1, 0
	ds_read_b128 v[28:31], v39 offset:53248
	s_waitcnt lgkmcnt(3)
	v_mfma_f32_16x16x32_bf16 v[2:5], v[2:5], v[20:23], v[12:15]
	s_nop 2
	ds_read_b128 v[12:15], v11 offset:64
	ds_read_b128 v[20:23], v37 offset:53312
	global_store_dwordx2 v[34:35], v[32:33], off sc0 sc1
	ds_read_b128 v[32:35], v39 offset:53312
	s_waitcnt lgkmcnt(4)
	v_mfma_f32_16x16x32_bf16 v[16:19], v[16:19], v[24:27], 0
	v_ashrrev_i32_e32 v37, 31, v36
	v_cvt_pk_bf16_f32 v38, v2, v3
	v_cvt_pk_bf16_f32 v39, v4, v5
	s_waitcnt lgkmcnt(3)
	v_mfma_f32_16x16x32_bf16 v[28:31], v[28:31], v[24:27], 0
	s_movk_i32 s6, 0x88
	s_waitcnt lgkmcnt(1)
	v_mfma_f32_16x16x32_bf16 v[2:5], v[20:23], v[12:15], v[16:19]
	s_nop 2
	v_lshl_add_u64 v[16:17], s[0:1], 0, v[36:37]
	global_store_dwordx2 v[16:17], v[38:39], off sc0 sc1
	s_waitcnt lgkmcnt(0)
	v_mfma_f32_16x16x32_bf16 v[16:19], v[32:35], v[12:15], v[28:31]
	s_lshl_b32 s0, s23, 1
	s_or_b32 s0, s0, 1
	v_xor_b32_e32 v11, 0x80000000, v5
	v_xor_b32_e32 v28, 0x80000000, v2
	v_xor_b32_e32 v22, 0x80000000, v4
	s_nop 2
	v_xor_b32_e32 v31, 0x80000000, v19
	v_lshl_or_b32 v19, s0, 5, v1
	v_mad_u32_u24 v2, v19, s8, v249
	v_mad_u32_u24 v9, v19, s8, v250
	v_lshl_add_u32 v10, v2, 1, 0
	v_lshl_add_u32 v9, v9, 1, 0
	v_xor_b32_e32 v23, 0x80000000, v3
	ds_read_b128 v[2:5], v10 offset:53248
	ds_read_b128 v[32:35], v10 offset:53312
	v_xor_b32_e32 v40, 0x80000000, v18
	ds_read_b128 v[18:21], v9 offset:53248
	ds_read_b128 v[36:39], v9 offset:53312
	v_xor_b32_e32 v17, 0x80000000, v17
	v_xor_b32_e32 v16, 0x80000000, v16
	s_waitcnt lgkmcnt(3)
	v_mfma_f32_16x16x32_bf16 v[2:5], v[2:5], v[24:27], 0
	v_cvt_pk_bf16_f32 v30, v16, v17
	v_lshl_or_b32 v10, s23, 11, v7
	v_cvt_pk_bf16_f32 v29, v22, v11
	s_waitcnt lgkmcnt(1)
	v_mfma_f32_16x16x32_bf16 v[16:19], v[18:21], v[24:27], 0
	v_ashrrev_i32_e32 v11, 31, v10
	v_cvt_pk_bf16_f32 v28, v28, v23
	v_cvt_pk_bf16_f32 v31, v40, v31
	v_lshl_add_u64 v[10:11], s[4:5], 0, v[10:11]
	v_mfma_f32_16x16x32_bf16 v[2:5], v[32:35], v[12:15], v[2:5]
	global_store_dwordx4 v[10:11], v[28:31], off sc0 sc1
	v_mov_b32_e32 v20, 0x990
	v_mov_b32_e32 v21, 0xa18
	s_waitcnt lgkmcnt(0)
	v_mfma_f32_16x16x32_bf16 v[10:13], v[36:39], v[12:15], v[16:19]
	v_and_b32_e32 v15, 12, v8
	s_nop 1
	v_xor_b32_e32 v5, 0x80000000, v5
	v_xor_b32_e32 v4, 0x80000000, v4
	v_xor_b32_e32 v3, 0x80000000, v3
	v_xor_b32_e32 v2, 0x80000000, v2
	s_nop 0
	v_xor_b32_e32 v11, 0x80000000, v11
	v_xor_b32_e32 v10, 0x80000000, v10
	v_cvt_pk_bf16_f32 v2, v2, v3
	v_cvt_pk_bf16_f32 v3, v4, v5
	v_cvt_pk_bf16_f32 v4, v10, v11
	v_lshl_or_b32 v10, s0, 10, v7
	v_xor_b32_e32 v9, 0x80000000, v13
	v_xor_b32_e32 v12, 0x80000000, v12
	v_ashrrev_i32_e32 v11, 31, v10
	v_cvt_pk_bf16_f32 v5, v12, v9
	v_lshl_add_u64 v[10:11], s[4:5], 0, v[10:11]
	global_store_dwordx4 v[10:11], v[2:5], off sc0 sc1
	v_lshrrev_b32_e32 v11, 1, v99
	v_and_b32_e32 v10, 0x60, v11
	v_ashrrev_i32_e32 v2, 4, v99
	v_and_or_b32 v2, v2, -16, v1
	v_lshl_add_u32 v7, v2, 2, s21
	v_mad_u64_u32 v[2:3], s[8:9], v2, s6, v[10:11]
	v_add_u32_e32 v3, v2, v15
	v_lshl_add_u32 v3, v3, 1, 0
	ds_read_b64 v[4:5], v3
	v_add_u32_e32 v18, 0x200, v99
	v_or_b32_e32 v16, 16, v15
	v_ashrrev_i32_e32 v3, 4, v18
	v_add_u32_e32 v2, v2, v16
	v_and_or_b32 v17, v3, -16, v1
	v_lshl_add_u32 v2, v2, 1, 0
	v_lshl_add_u32 v3, v17, 2, s21
	ds_read_b32 v8, v7
	ds_read_b64 v[12:13], v2
	ds_read_b32 v14, v3
	s_waitcnt lgkmcnt(3)
; #define LAS __attribute__((address_space(3)))
; __device__ __forceinline__ float bf2f(bf16_t b) { return __uint_as_float(((unsigned)b) << 16); }
; __device__ __forceinline__ void gdn_prep_item(LAS unsigned char* lds, int item, int b0, PrepRaw& R, int next_item, const bf16_t* qkv, const float* bg, const float* gconv_w, unsigned char* rec, float* gtarr) {
;     ...
;     for (int q = 0; q < 2; ++q) { const int task = tid + q * NTHREADS, fragi = task >> 6, ln = task & 63, lg = ln >> 4, l = ln & 15;
;         const int rt = fragi >> 2, s2 = fragi & 3, i = 16 * rt + l; const float e = EG[i];
;         const u32x2 lo = *(const LAS u32x2*)(lds + P2_QN + (i * 136 + 32 * s2 + 4 * lg) * 2), hi = *(const LAS u32x2*)(lds + P2_QN + (i * 136 + 32 * s2 + 16 + 4 * lg) * 2);
;         const unsigned vv[4] = {lo.x, lo.y, hi.x, hi.y}; u32x4 w; unsigned ww[4];
; #pragma unroll
;         for (int k2 = 0; k2 < 4; ++k2) ww[k2] = cvt_pk_bf16(__uint_as_float(vv[k2] << 16) * e, __uint_as_float(vv[k2] & 0xffff0000u) * e);
;         w.x = ww[0]; w.y = ww[1]; w.z = ww[2]; w.w = ww[3];
;         *(u32x4*)(rec + REC_QD + (fragi * 64 + ln) * 16) = w; }
; #pragma unroll
;     for (int q = 0; q < 2; ++q) { const int task = tid + q * NTHREADS, fragi = task >> 6, ln = task & 63, lg = ln >> 4, l = ln & 15;
;         const int dt = fragi >> 1, s = fragi & 1, dk = 16 * dt + l; float v[8];
; #pragma unroll
;         for (int j = 0; j < 8; ++j) { const int i = 32 * s + 4 * lg + (j & 3) + 16 * (j >> 2); v[j] = bf2f(*(const LAS bf16_t*)(lds + P2_KN + (i * 136 + dk) * 2)) * DKs[i]; }
;         u32x4 w; w.x = cvt_pk_bf16(v[0], v[1]); w.y = cvt_pk_bf16(v[2], v[3]); w.z = cvt_pk_bf16(v[4], v[5]); w.w = cvt_pk_bf16(v[6], v[7]);
;         *(u32x4*)(rec + REC_KDT + (fragi * 64 + ln) * 16) = w; }
;     __syncthreads();
; __device__ __forceinline__ void gdn_all(LAS unsigned char* lds, const XcdBarrier& xbar, const int G, const int bx, unsigned char* ws, float* out, const bf16_t* qkv, const float* bg, const float* gconv_w, ...
;     ...
;         asm volatile("s_waitcnt vmcnt(0)" ::: "memory"); __syncthreads();
;         if (threadIdx.x == 0) { __builtin_amdgcn_fence(__ATOMIC_RELEASE, "agent"); asm volatile("s_waitcnt vmcnt(0)" ::: "memory"); __hip_atomic_fetch_add(late_cnt, 1u, __ATOMIC_RELAXED, __HIP_MEMORY_SCOPE_AGENT); }
	v_lshlrev_b32_e32 v2, 16, v4
	v_and_b32_e32 v3, 0xffff0000, v4
	v_lshlrev_b32_e32 v4, 16, v5
	v_and_b32_e32 v5, 0xffff0000, v5
	s_waitcnt lgkmcnt(2)
	v_pk_mul_f32 v[2:3], v[8:9], v[2:3] op_sel_hi:[0,1]
	v_pk_mul_f32 v[4:5], v[8:9], v[4:5] op_sel_hi:[0,1]
	s_add_u32 s0, s4, 0x4000
	v_cvt_pk_bf16_f32 v2, v2, v3
	v_cvt_pk_bf16_f32 v3, v4, v5
	s_waitcnt lgkmcnt(1)
	v_lshlrev_b32_e32 v4, 16, v12
	v_and_b32_e32 v5, 0xffff0000, v12
	v_lshlrev_b32_e32 v12, 16, v13
	v_and_b32_e32 v13, 0xffff0000, v13
	s_addc_u32 s1, s5, 0
	v_pk_mul_f32 v[4:5], v[8:9], v[4:5] op_sel_hi:[0,1]
	v_pk_mul_f32 v[8:9], v[8:9], v[12:13] op_sel_hi:[0,1]
	v_ashrrev_i32_e32 v7, 31, v6
	v_cvt_pk_bf16_f32 v4, v4, v5
	v_cvt_pk_bf16_f32 v5, v8, v9
	v_lshl_add_u64 v[8:9], s[0:1], 0, v[6:7]
	global_store_dwordx4 v[8:9], v[2:5], off sc0 sc1
	v_mov_b32_e32 v19, 0x908
	v_mov_b32_e32 v13, 0x110
	v_mad_u64_u32 v[2:3], s[8:9], v17, s6, v[10:11]
	v_add_u32_e32 v3, v2, v15
	v_lshl_add_u32 v3, v3, 1, 0
	ds_read_b64 v[4:5], v3
	v_add_u32_e32 v2, v2, v16
	v_and_or_b32 v10, v11, 32, v15
	v_and_or_b32 v11, v98, -16, v1
	v_lshl_add_u32 v2, v2, 1, 0
	v_mad_u32_u24 v3, v10, s6, v11
	v_lshl_add_u32 v3, v3, 1, 0
	ds_read_b64 v[8:9], v2
	ds_read_u16 v12, v3 offset:17408
	s_waitcnt lgkmcnt(2)
	v_lshlrev_b32_e32 v2, 16, v4
	v_and_b32_e32 v3, 0xffff0000, v4
	v_lshlrev_b32_e32 v4, 16, v5
	v_and_b32_e32 v5, 0xffff0000, v5
	v_pk_mul_f32 v[2:3], v[14:15], v[2:3] op_sel_hi:[0,1]
	v_pk_mul_f32 v[4:5], v[14:15], v[4:5] op_sel_hi:[0,1]
	v_cvt_pk_bf16_f32 v2, v2, v3
	v_cvt_pk_bf16_f32 v3, v4, v5
	s_waitcnt lgkmcnt(1)
	v_lshlrev_b32_e32 v4, 16, v8
	v_and_b32_e32 v5, 0xffff0000, v8
	v_lshlrev_b32_e32 v8, 16, v9
	v_and_b32_e32 v9, 0xffff0000, v9
	v_lshlrev_b32_e32 v16, 4, v18
	v_pk_mul_f32 v[4:5], v[14:15], v[4:5] op_sel_hi:[0,1]
	v_pk_mul_f32 v[8:9], v[14:15], v[8:9] op_sel_hi:[0,1]
	v_ashrrev_i32_e32 v17, 31, v16
	v_cvt_pk_bf16_f32 v4, v4, v5
	v_cvt_pk_bf16_f32 v5, v8, v9
	v_lshl_add_u64 v[8:9], s[0:1], 0, v[16:17]
	v_mov_b32_e32 v14, 0x198
	global_store_dwordx4 v[8:9], v[2:5], off sc0 sc1
	v_mad_u32_u24 v22, v10, s6, s6
	v_mad_u32_u24 v24, v10, s6, v14
	v_lshl_add_u32 v2, v10, 2, 0
	v_mov_b32_e32 v15, 0x880
	v_mad_u32_u24 v26, v10, s6, v19
	v_mad_u32_u24 v27, v10, s6, v20
	v_ashrrev_i32_e32 v18, 3, v18
	v_add_u32_e32 v8, 0x1d300, v2
	v_add_u32_e32 v2, v22, v11
	v_mad_u32_u24 v23, v10, s6, v13
	v_add_u32_e32 v14, v24, v11
	v_mad_u32_u24 v25, v10, s6, v15
	v_add_u32_e32 v19, v26, v11
	v_add_u32_e32 v20, v27, v11
	v_mad_u32_u24 v28, v10, s6, v21
	v_and_or_b32 v1, v18, -16, v1
	v_lshl_add_u32 v9, v2, 1, 0
	v_add_u32_e32 v13, v23, v11
	v_lshl_add_u32 v14, v14, 1, 0
	v_add_u32_e32 v15, v25, v11
	v_lshl_add_u32 v19, v19, 1, 0
	v_lshl_add_u32 v20, v20, 1, 0
	v_add_u32_e32 v11, v28, v11
	v_mad_u32_u24 v10, v10, s6, v1
	ds_read_b128 v[2:5], v8
	v_lshl_add_u32 v13, v13, 1, 0
	v_lshl_add_u32 v15, v15, 1, 0
	v_lshl_add_u32 v11, v11, 1, 0
	v_lshl_add_u32 v10, v10, 1, 0
	ds_read_u16 v9, v9 offset:17408
	ds_read_u16 v18, v13 offset:17408
	ds_read_u16 v14, v14 offset:17408
	ds_read_u16 v21, v15 offset:17408
	ds_read_u16 v19, v19 offset:17408
	ds_read_u16 v20, v20 offset:17408
	ds_read_u16 v29, v11 offset:17408
	ds_read_u16 v30, v10 offset:17408
	s_waitcnt lgkmcnt(7)
	v_lshlrev_b32_e32 v13, 16, v9
	ds_read_b128 v[8:11], v8 offset:64
	s_add_u32 s0, s4, 0x8000
	v_lshlrev_b32_e32 v12, 16, v12
	s_waitcnt lgkmcnt(6)
	v_lshlrev_b32_e32 v15, 16, v14
	v_lshlrev_b32_e32 v14, 16, v18
	s_waitcnt lgkmcnt(4)
	v_lshlrev_b32_e32 v19, 16, v19
	v_lshlrev_b32_e32 v18, 16, v21
	s_waitcnt lgkmcnt(2)
	v_lshlrev_b32_e32 v21, 16, v29
	v_lshlrev_b32_e32 v20, 16, v20
	s_addc_u32 s1, s5, 0
	v_pk_mul_f32 v[12:13], v[2:3], v[12:13]
	v_pk_mul_f32 v[14:15], v[4:5], v[14:15]
	s_waitcnt lgkmcnt(0)
	v_pk_mul_f32 v[18:19], v[8:9], v[18:19]
	v_pk_mul_f32 v[20:21], v[10:11], v[20:21]
	v_cvt_pk_bf16_f32 v12, v12, v13
	v_cvt_pk_bf16_f32 v13, v14, v15
	v_cvt_pk_bf16_f32 v14, v18, v19
	v_cvt_pk_bf16_f32 v15, v20, v21
	v_lshl_add_u64 v[6:7], s[0:1], 0, v[6:7]
	global_store_dwordx4 v[6:7], v[12:15], off sc0 sc1
	v_add_u32_e32 v6, v22, v1
	v_add_u32_e32 v7, v23, v1
	v_add_u32_e32 v12, v24, v1
	v_add_u32_e32 v13, v25, v1
	v_add_u32_e32 v14, v26, v1
	v_add_u32_e32 v15, v27, v1
	v_add_u32_e32 v1, v28, v1
	v_lshl_add_u32 v6, v6, 1, 0
	v_lshl_add_u32 v12, v12, 1, 0
	v_lshl_add_u32 v13, v13, 1, 0
	v_lshl_add_u32 v14, v14, 1, 0
	v_lshl_add_u32 v15, v15, 1, 0
	v_lshl_add_u32 v1, v1, 1, 0
	v_lshl_add_u32 v7, v7, 1, 0
	ds_read_u16 v6, v6 offset:17408
	ds_read_u16 v18, v7 offset:17408
	ds_read_u16 v12, v12 offset:17408
	ds_read_u16 v13, v13 offset:17408
	ds_read_u16 v14, v14 offset:17408
	ds_read_u16 v15, v15 offset:17408
	ds_read_u16 v1, v1 offset:17408
	s_waitcnt lgkmcnt(6)
	v_lshlrev_b32_e32 v7, 16, v6
	v_lshlrev_b32_e32 v6, 16, v30
	v_pk_mul_f32 v[2:3], v[2:3], v[6:7]
	s_waitcnt lgkmcnt(4)
	v_lshlrev_b32_e32 v7, 16, v12
	v_lshlrev_b32_e32 v6, 16, v18
	v_pk_mul_f32 v[4:5], v[4:5], v[6:7]
	s_waitcnt lgkmcnt(2)
	v_lshlrev_b32_e32 v7, 16, v14
	v_lshlrev_b32_e32 v6, 16, v13
	v_pk_mul_f32 v[6:7], v[8:9], v[6:7]
	s_waitcnt lgkmcnt(0)
	v_lshlrev_b32_e32 v9, 16, v1
	v_lshlrev_b32_e32 v8, 16, v15
	v_pk_mul_f32 v[8:9], v[10:11], v[8:9]
	v_cvt_pk_bf16_f32 v2, v2, v3
	v_cvt_pk_bf16_f32 v3, v4, v5
	v_cvt_pk_bf16_f32 v4, v6, v7
	v_cvt_pk_bf16_f32 v5, v8, v9
	v_lshl_add_u64 v[6:7], s[0:1], 0, v[16:17]
	global_store_dwordx4 v[6:7], v[2:5], off sc0 sc1
	s_waitcnt vmcnt(0)
	s_barrier
	s_and_saveexec_b64 s[0:1], s[66:67]
	s_cbranch_execz .LBB0_703
	s_mov_b64 s[4:5], exec
	v_mbcnt_lo_u32_b32 v1, s4, 0
	s_nop 0
	s_waitcnt vmcnt(0)
	s_waitcnt vmcnt(0)
	v_mbcnt_hi_u32_b32 v1, s5, v1
	v_cmp_eq_u32_e32 vcc, 0, v1
	s_and_b64 s[6:7], exec, vcc
	s_mov_b64 exec, s[6:7]
	s_cbranch_execz .LBB0_703
	s_bcnt1_i32_b64 s4, s[4:5]
	v_mov_b32_e32 v1, s99
	v_lshlrev_b32_e32 v1, 2, v1
	v_mov_b32_e32 v2, s4
	global_atomic_add v1, v2, s[14:15]

; __device__ __forceinline__ unsigned xb_ld(unsigned* p)              { return __hip_atomic_load(p, __ATOMIC_RELAXED, __HIP_MEMORY_SCOPE_AGENT); }
; __device__ __forceinline__ unsigned xb_xcc_id() { return (unsigned)__builtin_amdgcn_s_getreg((3 << 11) | 20) & 0xFu; }
; template <class RecFn>
; __device__ __forceinline__ void gdn_scan(LAS unsigned char* lds, int bh, int b0, RecFn rec_of, const float* gtarr, bf16_t* zb, const float* gnorm_w, float* Sout, const unsigned* late_cnt, unsigned late_need, int cwait) {
;     ...
; #pragma unroll
;     for (int dt = 0; dt < 8; ++dt)
; #pragma unroll
;         for (int r = 0; r < 4; ++r) Sout[(size_t)(16 * dt + 4 * g + r) * DV + 16 * wave + l15] = S[dt][r];
;     __syncthreads();
; __device__ __forceinline__ void xcd_barrier_complete(unsigned* bar, unsigned x, unsigned& nloc, unsigned& nx) {
;     const unsigned G = gridDim.x * gridDim.y * gridDim.z;
;     unsigned sum, cnt, mine, sp = 0u;
;     for (;;) {
;         sum = 0u; cnt = 0u; mine = 0u;
; #pragma unroll
;         for (unsigned j = 0; j < 16; ++j) { const unsigned c = xb_ld(&bar[XB_XCNT(j)]); sum += c; cnt += (c > 0u) ? 1u : 0u; mine = (j == x) ? c : mine; }
;         if (sum == G) break;
;         __builtin_amdgcn_s_sleep(1);
;         if ((++sp & 255u) == 0u) { if (xb_ld(&bar[XB_TMO])) break; if (sp > XB_SPIN_CAP) { atomicAdd(&bar[XB_TMO], 1u); break; } }
;     }
;     nloc = mine > 0u ? mine : 1u; nx = cnt > 0u ? cnt : 1u;
; }
; __device__ __forceinline__ void xcd_barrier(const XcdBarrier& b) {
;     asm volatile("s_waitcnt vmcnt(0)" ::: "memory");
;     __syncthreads();
;     if (threadIdx.x == 0) {
;         unsigned* bar = b.bar;
;         unsigned bx_ = (unsigned)__builtin_amdgcn_readfirstlane((int)xb_xcc_id()); asm volatile("" : "+s"(bx_));
;         __builtin_amdgcn_s_waitcnt(0);
;         unsigned nloc = b.st[0], nx = b.st[1];
;         if (nloc == 0u) { xcd_barrier_complete(bar, bx_, nloc, nx); b.st[0] = nloc; b.st[1] = nx; }
.LBB0_790:
	s_or_b64 exec, exec, s[0:1]
	v_readlane_b32 s36, v245, 19
	s_lshl_b64 s[0:1], s[94:95], 16
	v_readlane_b32 s48, v245, 31
	v_readlane_b32 s49, v245, 32
	s_add_u32 s2, s48, s0
	s_addc_u32 s3, s49, s1
	s_ashr_i32 s17, s16, 31
	s_lshl_b64 s[0:1], s[16:17], 2
	s_add_u32 s0, s2, s0
	s_addc_u32 s1, s3, s1
	v_lshlrev_b32_e32 v34, 2, v1
	v_lshlrev_b32_e32 v36, 9, v77
	v_lshl_add_u64 v[38:39], s[0:1], 0, v[34:35]
	s_mov_b64 s[0:1], 0x4448000
	v_lshl_add_u64 v[38:39], v[38:39], 0, s[0:1]
	v_mov_b32_e32 v37, v35
	v_or_b32_e32 v34, 0x200, v36
	v_lshl_add_u64 v[40:41], v[38:39], 0, v[36:37]
	v_lshl_add_u64 v[42:43], v[38:39], 0, v[34:35]
	v_or_b32_e32 v34, 0x400, v36
	global_store_dword v[40:41], v30, off
	global_store_dword v[42:43], v31, off
	v_lshl_add_u64 v[30:31], v[38:39], 0, v[34:35]
	v_or_b32_e32 v34, 0x600, v36
	global_store_dword v[30:31], v32, off
	v_lshl_add_u64 v[30:31], v[38:39], 0, v[34:35]
	v_or_b32_e32 v34, 0x2000, v36
	global_store_dword v[30:31], v33, off
	v_lshl_add_u64 v[30:31], v[38:39], 0, v[34:35]
	v_or_b32_e32 v34, 0x2200, v36
	global_store_dword v[30:31], v26, off
	v_lshl_add_u64 v[30:31], v[38:39], 0, v[34:35]
	v_or_b32_e32 v34, 0x2400, v36
	global_store_dword v[30:31], v27, off
	v_lshl_add_u64 v[26:27], v[38:39], 0, v[34:35]
	v_or_b32_e32 v34, 0x2600, v36
	global_store_dword v[26:27], v28, off
	v_lshl_add_u64 v[26:27], v[38:39], 0, v[34:35]
	v_or_b32_e32 v34, 0x4000, v36
	global_store_dword v[26:27], v29, off
	v_lshl_add_u64 v[26:27], v[38:39], 0, v[34:35]
	v_or_b32_e32 v34, 0x4200, v36
	global_store_dword v[26:27], v22, off
	v_lshl_add_u64 v[26:27], v[38:39], 0, v[34:35]
	v_or_b32_e32 v34, 0x4400, v36
	global_store_dword v[26:27], v23, off
	v_lshl_add_u64 v[22:23], v[38:39], 0, v[34:35]
	v_or_b32_e32 v34, 0x4600, v36
	global_store_dword v[22:23], v24, off
	v_lshl_add_u64 v[22:23], v[38:39], 0, v[34:35]
	v_or_b32_e32 v34, 0x6000, v36
	global_store_dword v[22:23], v25, off
	v_lshl_add_u64 v[22:23], v[38:39], 0, v[34:35]
	v_or_b32_e32 v34, 0x6200, v36
	global_store_dword v[22:23], v2, off
	v_lshl_add_u64 v[22:23], v[38:39], 0, v[34:35]
	v_or_b32_e32 v34, 0x6400, v36
	global_store_dword v[22:23], v3, off
	v_lshl_add_u64 v[2:3], v[38:39], 0, v[34:35]
	v_or_b32_e32 v34, 0x6600, v36
	global_store_dword v[2:3], v4, off
	v_lshl_add_u64 v[2:3], v[38:39], 0, v[34:35]
	s_mov_b32 s0, 0x8000
	global_store_dword v[2:3], v5, off
	v_add_co_u32_e32 v2, vcc, s0, v40
	s_mov_b32 s0, 0xa000
	s_nop 0
	v_addc_co_u32_e32 v3, vcc, 0, v41, vcc
	global_store_dword v[2:3], v10, off
	global_store_dword v[2:3], v11, off offset:512
	global_store_dword v[2:3], v12, off offset:1024
	global_store_dword v[2:3], v13, off offset:1536
	v_add_co_u32_e32 v2, vcc, s0, v40
	s_mov_b32 s0, 0xc000
	s_nop 0
	v_addc_co_u32_e32 v3, vcc, 0, v41, vcc
	global_store_dword v[2:3], v18, off
	global_store_dword v[2:3], v19, off offset:512
	global_store_dword v[2:3], v20, off offset:1024
	global_store_dword v[2:3], v21, off offset:1536
	v_add_co_u32_e32 v2, vcc, s0, v40
	v_readlane_b32 s37, v245, 20
	s_nop 0
	v_addc_co_u32_e32 v3, vcc, 0, v41, vcc
	global_store_dword v[2:3], v14, off
	global_store_dword v[2:3], v15, off offset:512
	global_store_dword v[2:3], v16, off offset:1024
	global_store_dword v[2:3], v17, off offset:1536
	v_add_co_u32_e32 v2, vcc, 0xe000, v40
	v_readlane_b32 s38, v245, 21
	s_nop 0
	v_addc_co_u32_e32 v3, vcc, 0, v41, vcc
	v_readlane_b32 s39, v245, 22
	v_readlane_b32 s40, v245, 23
	v_readlane_b32 s41, v245, 24
	v_readlane_b32 s42, v245, 25
	v_readlane_b32 s43, v245, 26
	v_readlane_b32 s44, v245, 27
	v_readlane_b32 s45, v245, 28
	v_readlane_b32 s46, v245, 29
	v_readlane_b32 s47, v245, 30
	v_readlane_b32 s50, v245, 33
	v_readlane_b32 s51, v245, 34
	global_store_dword v[2:3], v6, off
	global_store_dword v[2:3], v7, off offset:512
	global_store_dword v[2:3], v8, off offset:1024
	global_store_dword v[2:3], v9, off offset:1536
	s_waitcnt lgkmcnt(0)
.LBB0_791:
	s_waitcnt vmcnt(0)
	s_barrier
	s_and_saveexec_b64 s[0:1], s[66:67]
	s_cbranch_execz .LBB0_843
	s_getreg_b32 s2, hwreg(HW_REG_XCC_ID, 0, 4)
	s_add_i32 s3, 0, 0x27fc0
	s_and_b32 s2, s2, 15
	v_mov_b32_e32 v1, s3
	s_waitcnt vmcnt(0) expcnt(0) lgkmcnt(0)
	ds_read_b32 v3, v1
	s_add_i32 s3, 0, 0x27fc4
	v_mov_b32_e32 v1, s3
	ds_read_b32 v1, v1
	s_waitcnt lgkmcnt(1)
	v_cmp_ne_u32_e32 vcc, 0, v3
	s_cbranch_vccnz .LBB0_807
	v_readlane_b32 s12, v245, 19
	v_readlane_b32 s26, v245, 33
	v_readlane_b32 s27, v245, 34
	s_add_u32 s4, s26, 0x1200
	s_addc_u32 s5, s27, 0
	s_add_u32 s6, s26, 0x1400
	s_addc_u32 s7, s27, 0
	s_add_u32 s8, s26, 0x1500
	s_addc_u32 s9, s27, 0
	v_readlane_b32 s13, v245, 20
	s_add_u32 s12, s26, 0x1600
	v_readlane_b32 s14, v245, 21
	s_addc_u32 s13, s27, 0
	v_readlane_b32 s15, v245, 22
	s_add_u32 s14, s26, 0x1700
	v_readlane_b32 s16, v245, 23
	s_addc_u32 s15, s27, 0
	v_readlane_b32 s17, v245, 24
	s_add_u32 s16, s26, 0x1800
	v_readlane_b32 s18, v245, 25
	s_addc_u32 s17, s27, 0
	v_readlane_b32 s19, v245, 26
	s_add_u32 s18, s26, 0x1900
	v_readlane_b32 s20, v245, 27
	s_addc_u32 s19, s27, 0
	v_readlane_b32 s21, v245, 28
	s_add_u32 s20, s26, 0x1a00
	v_readlane_b32 s22, v245, 29
	s_addc_u32 s21, s27, 0
	v_readlane_b32 s23, v245, 30
	s_add_u32 s22, s26, 0x1b00
	v_readlane_b32 s24, v245, 31
	s_addc_u32 s23, s27, 0
	v_readlane_b32 s25, v245, 32
	s_add_u32 s24, s26, 0x1c00
	s_addc_u32 s25, s27, 0
	s_add_u32 s28, s26, 0x1d00
	s_addc_u32 s29, s27, 0
	s_add_u32 s30, s26, 0x1e00
	s_addc_u32 s31, s27, 0
	s_add_u32 s34, s26, 0x1f00
	s_addc_u32 s35, s27, 0
	s_add_u32 s36, s26, 0x2000
	s_addc_u32 s37, s27, 0
	s_add_u32 s38, s26, 0x2100
	s_addc_u32 s39, s27, 0
	s_add_u32 s40, s26, 0x2200
	s_addc_u32 s41, s27, 0
	s_mul_i32 s3, s97, s93
	s_add_u32 s42, s26, 0x2300
	s_mul_i32 s3, s3, s96
	s_addc_u32 s43, s27, 0
	s_mov_b32 s26, 1
	v_mov_b32_e32 v17, 0
	s_branch .LBB0_795

; #define PG8_WAIT_V(n) asm volatile("s_waitcnt vmcnt(" #n ")" ::: "memory")
; #define PG8_BAR __builtin_amdgcn_s_barrier()
; __device__ __forceinline__ unsigned xb_xcc_id() { return (unsigned)__builtin_amdgcn_s_getreg((3 << 11) | 20) & 0xFu; }
; template <class Epi, bool ALIGN_EPI, bool SP2, class Ord = StaticOrder>
; __device__ __forceinline__ void gemm_phase(LAS unsigned char* lds, const Gemm g, const Ord& S, const Epi& E) {
;     ...
;     PG8_WAIT_V(0);
;     if constexpr (!ALIGN_EPI) { if (wr == 0) PG8_BAR; }
;     PG8_BAR;
; __device__ __forceinline__ void xcd_barrier(const XcdBarrier& b) {
;     asm volatile("s_waitcnt vmcnt(0)" ::: "memory");
;     __syncthreads();
;     if (threadIdx.x == 0) {
;         unsigned* bar = b.bar;
;         unsigned bx_ = (unsigned)__builtin_amdgcn_readfirstlane((int)xb_xcc_id()); asm volatile("" : "+s"(bx_));
;         __builtin_amdgcn_s_waitcnt(0);
;         unsigned nloc = b.st[0], nx = b.st[1];
;         if (nloc == 0u) { xcd_barrier_complete(bar, bx_, nloc, nx); b.st[0] = nloc; b.st[1] = nx; }
.LBB0_1852:
	s_waitcnt vmcnt(0)
	v_readlane_b32 s38, v239, 2
	v_readlane_b32 s40, v239, 4
	v_readlane_b32 s42, v239, 6
	v_readlane_b32 s46, v239, 8
	v_readlane_b32 s48, v239, 10
	v_readlane_b32 s34, v239, 12
	v_readlane_b32 s39, v239, 3
	v_readlane_b32 s41, v239, 5
	v_readlane_b32 s43, v239, 7
	v_readlane_b32 s47, v239, 9
	v_readlane_b32 s49, v239, 11
	v_readlane_b32 s35, v239, 13
	v_readlane_b32 s28, v239, 16
	v_readlane_b32 s33, v239, 17
.LBB0_1853:
	s_waitcnt vmcnt(0)
	s_waitcnt lgkmcnt(0)
	s_barrier
	s_and_saveexec_b64 s[0:1], s[74:75]
	v_readlane_b32 s52, v245, 36
	s_cbranch_execz .LBB0_1084
	s_getreg_b32 s2, hwreg(HW_REG_XCC_ID, 0, 4)
	v_readlane_b32 s3, v244, 56
	s_and_b32 s2, s2, 15
	s_waitcnt vmcnt(0) expcnt(0) lgkmcnt(0)
	v_mov_b32_e32 v2, s3
	ds_read_b32 v4, v2
	v_readlane_b32 s3, v244, 57
	s_waitcnt lgkmcnt(0)
	v_cmp_ne_u32_e32 vcc, 0, v4
	v_mov_b32_e32 v2, s3
	ds_read_b32 v2, v2
	s_cbranch_vccnz .LBB0_1869
	s_mov_b32 s3, 1
	s_branch .LBB0_1857
